# vAA + nt on the prologue's read-once conversion loads (layer-0 weights part 1 and the f32 input)
# speedup vs baseline: 1.0130x; 1.0130x over previous
.LBB0_6:
	s_mul_hi_i32 s14, s86, 0x66666667
	s_lshr_b32 s15, s14, 31
	s_ashr_i32 s14, s14, 5
	s_add_i32 s17, s14, s15
	s_lshl_b32 s14, s17, 6
	s_mul_i32 s15, s17, 0xffffec00
	s_add_i32 s16, s3, s15
	s_ashr_i32 s15, s14, 31
	s_mul_i32 s17, s17, 0x140000
	s_mul_hi_i32 s18, s14, 0x5000
	s_add_u32 s87, s6, s17
	s_addc_u32 s88, s7, s18
	s_ashr_i32 s17, s16, 31
	s_lshl_b64 s[18:19], s[16:17], 2
	s_add_u32 s18, s87, s18
	s_addc_u32 s19, s88, s19
	v_lshl_add_u64 v[6:7], s[18:19], 0, v[4:5]
	v_add_co_u32_e32 v70, vcc, s21, v6
	s_nop 1
	v_addc_co_u32_e32 v71, vcc, 0, v7, vcc
	v_add_co_u32_e32 v64, vcc, s22, v6
	s_nop 1
	v_addc_co_u32_e32 v65, vcc, 0, v7, vcc
	v_add_co_u32_e32 v66, vcc, s23, v6
	s_nop 1
	v_addc_co_u32_e32 v67, vcc, 0, v7, vcc
	v_add_co_u32_e32 v68, vcc, s24, v6
	s_nop 1
	v_addc_co_u32_e32 v69, vcc, 0, v7, vcc
	v_add_co_u32_e32 v72, vcc, s25, v6
	s_nop 1
	v_addc_co_u32_e32 v73, vcc, 0, v7, vcc
	v_add_co_u32_e32 v74, vcc, s26, v6
	s_nop 1
	v_addc_co_u32_e32 v75, vcc, 0, v7, vcc
	v_add_co_u32_e32 v76, vcc, s27, v6
	s_nop 1
	v_addc_co_u32_e32 v77, vcc, 0, v7, vcc
	v_add_co_u32_e32 v78, vcc, s28, v6
	s_nop 1
	v_addc_co_u32_e32 v79, vcc, 0, v7, vcc
	v_add_co_u32_e32 v62, vcc, s29, v6
	s_nop 1
	v_addc_co_u32_e32 v63, vcc, 0, v7, vcc
	v_add_co_u32_e32 v56, vcc, s30, v6
	s_nop 1
	v_addc_co_u32_e32 v57, vcc, 0, v7, vcc
	v_add_co_u32_e32 v58, vcc, s31, v6
	s_nop 1
	v_addc_co_u32_e32 v59, vcc, 0, v7, vcc
	v_add_co_u32_e32 v60, vcc, s34, v6
	s_nop 1
	v_addc_co_u32_e32 v61, vcc, 0, v7, vcc
	v_add_co_u32_e32 v80, vcc, s35, v6
	s_nop 1
	v_addc_co_u32_e32 v81, vcc, 0, v7, vcc
	v_add_co_u32_e32 v82, vcc, s36, v6
	s_nop 1
	v_addc_co_u32_e32 v83, vcc, 0, v7, vcc
	v_add_co_u32_e32 v84, vcc, s37, v6
	s_nop 1
	v_addc_co_u32_e32 v85, vcc, 0, v7, vcc
	v_add_co_u32_e32 v86, vcc, s38, v6
	s_nop 1
	v_addc_co_u32_e32 v87, vcc, 0, v7, vcc
	v_add_co_u32_e32 v54, vcc, s39, v6
	s_nop 1
	v_addc_co_u32_e32 v55, vcc, 0, v7, vcc
	v_add_co_u32_e32 v48, vcc, s40, v6
	s_nop 1
	v_addc_co_u32_e32 v49, vcc, 0, v7, vcc
	v_add_co_u32_e32 v50, vcc, s41, v6
	s_nop 1
	v_addc_co_u32_e32 v51, vcc, 0, v7, vcc
	v_add_co_u32_e32 v52, vcc, s42, v6
	s_nop 1
	v_addc_co_u32_e32 v53, vcc, 0, v7, vcc
	v_add_co_u32_e32 v88, vcc, s43, v6
	s_nop 1
	v_addc_co_u32_e32 v89, vcc, 0, v7, vcc
	v_add_co_u32_e32 v90, vcc, s44, v6
	s_nop 1
	v_addc_co_u32_e32 v91, vcc, 0, v7, vcc
	v_add_co_u32_e32 v92, vcc, s45, v6
	s_nop 1
	v_addc_co_u32_e32 v93, vcc, 0, v7, vcc
	v_add_co_u32_e32 v38, vcc, s48, v6
	s_nop 1
	v_addc_co_u32_e32 v39, vcc, 0, v7, vcc
	v_add_co_u32_e32 v40, vcc, s49, v6
	s_nop 1
	v_addc_co_u32_e32 v41, vcc, 0, v7, vcc
	v_add_co_u32_e32 v44, vcc, s50, v6
	s_nop 1
	v_addc_co_u32_e32 v45, vcc, 0, v7, vcc
	v_add_co_u32_e32 v46, vcc, s51, v6
	s_nop 1
	v_addc_co_u32_e32 v47, vcc, 0, v7, vcc
	v_add_co_u32_e32 v94, vcc, s52, v6
	s_nop 1
	v_addc_co_u32_e32 v95, vcc, 0, v7, vcc
	v_add_co_u32_e32 v96, vcc, s53, v6
	s_nop 1
	v_addc_co_u32_e32 v97, vcc, 0, v7, vcc
	v_add_co_u32_e32 v30, vcc, s56, v6
	s_nop 1
	v_addc_co_u32_e32 v31, vcc, 0, v7, vcc
	v_add_co_u32_e32 v32, vcc, s57, v6
	s_nop 1
	v_addc_co_u32_e32 v33, vcc, 0, v7, vcc
	v_add_co_u32_e32 v34, vcc, s59, v6
	s_nop 1
	v_addc_co_u32_e32 v35, vcc, 0, v7, vcc
	v_add_co_u32_e32 v36, vcc, s60, v6
	s_nop 1
	v_addc_co_u32_e32 v37, vcc, 0, v7, vcc
	v_add_co_u32_e32 v98, vcc, s61, v6
	s_nop 1
	v_addc_co_u32_e32 v99, vcc, 0, v7, vcc
	v_add_co_u32_e32 v100, vcc, s62, v6
	s_nop 1
	v_addc_co_u32_e32 v101, vcc, 0, v7, vcc
	v_add_co_u32_e32 v22, vcc, s65, v6
	s_nop 1
	v_addc_co_u32_e32 v23, vcc, 0, v7, vcc
	v_add_co_u32_e32 v24, vcc, s66, v6
	s_nop 1
	v_addc_co_u32_e32 v25, vcc, 0, v7, vcc
	v_add_co_u32_e32 v26, vcc, s67, v6
	s_nop 1
	v_addc_co_u32_e32 v27, vcc, 0, v7, vcc
	v_add_co_u32_e32 v28, vcc, s68, v6
	s_nop 1
	v_addc_co_u32_e32 v29, vcc, 0, v7, vcc
	v_add_co_u32_e32 v102, vcc, s69, v6
	s_nop 1
	v_addc_co_u32_e32 v103, vcc, 0, v7, vcc
	v_add_co_u32_e32 v104, vcc, s70, v6
	s_nop 1
	v_addc_co_u32_e32 v105, vcc, 0, v7, vcc
	v_add_co_u32_e32 v14, vcc, s73, v6
	s_nop 1
	v_addc_co_u32_e32 v15, vcc, 0, v7, vcc
	v_add_co_u32_e32 v16, vcc, s76, v6
	s_nop 1
	v_addc_co_u32_e32 v17, vcc, 0, v7, vcc
	v_add_co_u32_e32 v18, vcc, s77, v6
	s_nop 1
	v_addc_co_u32_e32 v19, vcc, 0, v7, vcc
	v_add_co_u32_e32 v20, vcc, s78, v6
	s_nop 1
	v_addc_co_u32_e32 v21, vcc, 0, v7, vcc
	v_add_co_u32_e32 v106, vcc, s79, v6
	s_nop 1
	v_addc_co_u32_e32 v107, vcc, 0, v7, vcc
	v_add_co_u32_e32 v108, vcc, s80, v6
	s_nop 1
	v_addc_co_u32_e32 v109, vcc, 0, v7, vcc
	v_add_co_u32_e32 v110, vcc, s46, v6
	s_nop 1
	v_addc_co_u32_e32 v111, vcc, 0, v7, vcc
	v_add_co_u32_e32 v112, vcc, s47, v6
	s_nop 1
	v_addc_co_u32_e32 v113, vcc, 0, v7, vcc
	v_add_co_u32_e32 v114, vcc, s54, v6
	s_nop 1
	v_addc_co_u32_e32 v115, vcc, 0, v7, vcc
	v_add_co_u32_e32 v116, vcc, s55, v6
	s_nop 1
	v_addc_co_u32_e32 v117, vcc, 0, v7, vcc
	v_add_co_u32_e32 v118, vcc, s63, v6
	s_nop 1
	v_addc_co_u32_e32 v119, vcc, 0, v7, vcc
	v_add_co_u32_e32 v120, vcc, s64, v6
	s_nop 1
	v_addc_co_u32_e32 v121, vcc, 0, v7, vcc
	v_add_co_u32_e32 v122, vcc, s71, v6
	s_nop 1
	v_addc_co_u32_e32 v123, vcc, 0, v7, vcc
	v_add_co_u32_e32 v124, vcc, s72, v6
	s_nop 1
	v_addc_co_u32_e32 v125, vcc, 0, v7, vcc
	v_add_co_u32_e32 v126, vcc, s81, v6
	s_nop 1
	v_addc_co_u32_e32 v127, vcc, 0, v7, vcc
	v_add_co_u32_e32 v12, vcc, s82, v6
	s_nop 1
	v_addc_co_u32_e32 v13, vcc, 0, v7, vcc
	v_add_co_u32_e32 v8, vcc, s83, v6
	s_nop 1
	v_addc_co_u32_e32 v9, vcc, 0, v7, vcc
	v_add_co_u32_e32 v10, vcc, s84, v6
	s_nop 1
	v_addc_co_u32_e32 v11, vcc, 0, v7, vcc
	v_add_co_u32_e32 v42, vcc, s85, v6
	s_nop 1
	v_addc_co_u32_e32 v43, vcc, 0, v7, vcc
	v_add_co_u32_e32 v128, vcc, 0x131000, v6
	s_nop 1
	v_addc_co_u32_e32 v129, vcc, 0, v7, vcc
	v_add_co_u32_e32 v130, vcc, 0x136000, v6
	s_nop 1
	v_addc_co_u32_e32 v131, vcc, 0, v7, vcc
	v_add_co_u32_e32 v132, vcc, 0x13b000, v6
	s_nop 1
	v_addc_co_u32_e32 v133, vcc, 0, v7, vcc
	global_load_dword v6, v[8:9], off nt
	global_load_dword v7, v[10:11], off nt
	s_nop 0
	global_load_dword v8, v[42:43], off nt
	global_load_dword v9, v[128:129], off nt
	global_load_dword v10, v[130:131], off nt
	global_load_dword v11, v[132:133], off nt
	s_nop 0
	global_load_dword v42, v4, s[18:19] nt
	s_nop 0
	global_load_dword v13, v[12:13], off nt
	s_nop 0
	global_load_dword v14, v[14:15], off nt
	s_nop 0
	global_load_dword v15, v[16:17], off nt
	s_nop 0
	global_load_dword v16, v[18:19], off nt
	global_load_dword v17, v[20:21], off nt
	s_nop 0
	global_load_dword v18, v[106:107], off nt
	global_load_dword v19, v[108:109], off nt
	global_load_dword v12, v[126:127], off nt
	global_load_dword v21, v[124:125], off nt
	s_nop 0
	global_load_dword v22, v[22:23], off nt
	s_nop 0
	global_load_dword v23, v[24:25], off nt
	s_nop 0
	global_load_dword v24, v[26:27], off nt
	global_load_dword v25, v[28:29], off nt
	s_nop 0
	global_load_dword v26, v[102:103], off nt
	global_load_dword v27, v[104:105], off nt
	global_load_dword v20, v[122:123], off nt
	global_load_dword v29, v[120:121], off nt
	s_nop 0
	global_load_dword v30, v[30:31], off nt
	s_nop 0
	global_load_dword v31, v[32:33], off nt
	s_nop 0
	global_load_dword v32, v[34:35], off nt
	global_load_dword v33, v[36:37], off nt
	s_nop 0
	global_load_dword v34, v[98:99], off nt
	global_load_dword v35, v[100:101], off nt
	global_load_dword v28, v[118:119], off nt
	global_load_dword v37, v[116:117], off nt
	s_nop 0
	global_load_dword v38, v[38:39], off nt
	s_nop 0
	global_load_dword v39, v[40:41], off nt
	s_nop 0
	global_load_dword v40, v[44:45], off nt
	global_load_dword v41, v[46:47], off nt
	s_nop 0
	global_load_dword v44, v[94:95], off nt
	global_load_dword v45, v[96:97], off nt
	global_load_dword v36, v[114:115], off nt
	global_load_dword v47, v[112:113], off nt
	s_nop 0
	global_load_dword v48, v[48:49], off nt
	s_nop 0
	global_load_dword v49, v[50:51], off nt
	s_nop 0
	global_load_dword v50, v[52:53], off nt
	global_load_dword v51, v[88:89], off nt
	s_nop 0
	global_load_dword v52, v[90:91], off nt
	global_load_dword v53, v[92:93], off nt
	global_load_dword v46, v[110:111], off nt
	s_nop 0
	global_load_dword v55, v[54:55], off nt
	s_nop 0
	global_load_dword v56, v[56:57], off nt
	s_nop 0
	global_load_dword v57, v[58:59], off nt
	s_nop 0
	global_load_dword v58, v[60:61], off nt
	global_load_dword v59, v[80:81], off nt
	s_nop 0
	global_load_dword v60, v[82:83], off nt
	global_load_dword v61, v[84:85], off nt
	global_load_dword v54, v[86:87], off nt
	s_nop 0
	global_load_dword v63, v[62:63], off nt
	s_nop 0
	global_load_dword v64, v[64:65], off nt
	s_nop 0
	global_load_dword v65, v[66:67], off nt
	s_nop 0
	global_load_dword v66, v[68:69], off nt
	global_load_dword v67, v[72:73], off nt
	s_nop 0
	global_load_dword v68, v[74:75], off nt
	global_load_dword v69, v[76:77], off nt
	global_load_dword v62, v[78:79], off nt
	global_load_dword v43, v[70:71], off nt
	s_andn2_b64 vcc, exec, s[12:13]
	s_cbranch_vccnz .LBB0_5
	s_lshl_b64 s[18:19], s[14:15], 2
	s_add_u32 s18, s4, s18
	s_addc_u32 s19, s5, s19
	global_load_dwordx4 v[70:73], v5, s[18:19] nt
	global_load_dwordx4 v[74:77], v5, s[18:19] offset:16 nt
	global_load_dwordx4 v[78:81], v5, s[18:19] offset:32 nt
	global_load_dwordx4 v[82:85], v5, s[18:19] offset:48 nt
	global_load_dwordx4 v[86:89], v5, s[18:19] offset:64 nt
	global_load_dwordx4 v[90:93], v5, s[18:19] offset:80 nt
	global_load_dwordx4 v[94:97], v5, s[18:19] offset:96 nt
	global_load_dwordx4 v[98:101], v5, s[18:19] offset:112 nt
	global_load_dwordx4 v[102:105], v5, s[18:19] offset:128 nt
	global_load_dwordx4 v[106:109], v5, s[18:19] offset:144 nt
	global_load_dwordx4 v[110:113], v5, s[18:19] offset:160 nt
	global_load_dwordx4 v[114:117], v5, s[18:19] offset:176 nt
	global_load_dwordx4 v[118:121], v5, s[18:19] offset:192 nt
	global_load_dwordx4 v[122:125], v5, s[18:19] offset:208 nt
	global_load_dwordx4 v[126:129], v5, s[18:19] offset:224 nt
	global_load_dwordx4 v[130:133], v5, s[18:19] offset:240 nt
	s_waitcnt vmcnt(15)
	v_pk_mul_f32 v[42:43], v[42:43], v[70:71]
	v_pk_mul_f32 v[64:65], v[64:65], v[72:73]
	s_waitcnt vmcnt(14)
	v_pk_mul_f32 v[66:67], v[66:67], v[74:75]
	v_pk_mul_f32 v[68:69], v[68:69], v[76:77]
	s_waitcnt vmcnt(13)
	v_pk_mul_f32 v[62:63], v[62:63], v[78:79]
	v_pk_mul_f32 v[56:57], v[56:57], v[80:81]
	s_waitcnt vmcnt(12)
	v_pk_mul_f32 v[58:59], v[58:59], v[82:83]
	v_pk_mul_f32 v[60:61], v[60:61], v[84:85]
	s_waitcnt vmcnt(11)
	v_pk_mul_f32 v[54:55], v[54:55], v[86:87]
	v_pk_mul_f32 v[48:49], v[48:49], v[88:89]
	s_waitcnt vmcnt(10)
	v_pk_mul_f32 v[50:51], v[50:51], v[90:91]
	v_pk_mul_f32 v[52:53], v[52:53], v[92:93]
	s_waitcnt vmcnt(9)
	v_pk_mul_f32 v[46:47], v[46:47], v[94:95]
	v_pk_mul_f32 v[38:39], v[38:39], v[96:97]
	s_waitcnt vmcnt(8)
	v_pk_mul_f32 v[40:41], v[40:41], v[98:99]
	v_pk_mul_f32 v[44:45], v[44:45], v[100:101]
	s_waitcnt vmcnt(7)
	v_pk_mul_f32 v[36:37], v[36:37], v[102:103]
	v_pk_mul_f32 v[30:31], v[30:31], v[104:105]
	s_waitcnt vmcnt(6)
	v_pk_mul_f32 v[32:33], v[32:33], v[106:107]
	v_pk_mul_f32 v[34:35], v[34:35], v[108:109]
	s_waitcnt vmcnt(5)
	v_pk_mul_f32 v[28:29], v[28:29], v[110:111]
	v_pk_mul_f32 v[22:23], v[22:23], v[112:113]
	s_waitcnt vmcnt(4)
	v_pk_mul_f32 v[24:25], v[24:25], v[114:115]
	v_pk_mul_f32 v[26:27], v[26:27], v[116:117]
	s_waitcnt vmcnt(3)
	v_pk_mul_f32 v[20:21], v[20:21], v[118:119]
	v_pk_mul_f32 v[14:15], v[14:15], v[120:121]
	s_waitcnt vmcnt(2)
	v_pk_mul_f32 v[16:17], v[16:17], v[122:123]
	v_pk_mul_f32 v[18:19], v[18:19], v[124:125]
	s_waitcnt vmcnt(1)
	v_pk_mul_f32 v[12:13], v[12:13], v[126:127]
	v_pk_mul_f32 v[6:7], v[6:7], v[128:129]
	s_waitcnt vmcnt(0)
	v_pk_mul_f32 v[8:9], v[8:9], v[130:131]
	v_pk_mul_f32 v[10:11], v[10:11], v[132:133]
	s_branch .LBB0_5

.LBB0_13:
	s_ashr_i32 s11, s10, 31
	s_add_i32 s18, s36, s10
	s_cmpk_lt_i32 s18, 0x4000
	s_cselect_b64 s[22:23], -1, 0
	s_and_b64 s[12:13], s[22:23], exec
	s_cselect_b32 s12, s18, s10
	s_ashr_i32 s13, s12, 31
	s_lshl_b64 s[24:25], s[12:13], 12
	s_add_i32 s14, s26, s10
	s_cmpk_lt_i32 s14, 0x4000
	s_cselect_b64 s[20:21], -1, 0
	s_and_b64 s[12:13], s[20:21], exec
	s_cselect_b32 s12, s14, s10
	s_ashr_i32 s13, s12, 31
	s_lshl_b64 s[28:29], s[12:13], 12
	s_add_i32 s12, s27, s10
	s_cmpk_lt_i32 s12, 0x4000
	s_cselect_b64 s[16:17], -1, 0
	s_and_b64 s[30:31], s[16:17], exec
	s_cselect_b32 s30, s12, s10
	s_lshl_b64 s[34:35], s[10:11], 12
	s_waitcnt vmcnt(4)
	v_lshl_add_u64 v[2:3], v[50:51], 0, s[34:35]
	s_waitcnt lgkmcnt(0)
	global_load_dwordx4 v[70:73], v[2:3], off nt
	global_load_dwordx4 v[74:77], v[2:3], off offset:1024 nt
	global_load_dwordx4 v[78:81], v[2:3], off offset:2048 nt
	global_load_dwordx4 v[82:85], v[2:3], off offset:3072 nt
	s_ashr_i32 s31, s30, 31
	v_lshl_add_u64 v[2:3], v[50:51], 0, s[24:25]
	s_lshl_b64 s[24:25], s[30:31], 12
	global_load_dwordx4 v[46:49], v[2:3], off nt
	global_load_dwordx4 v[42:45], v[2:3], off offset:1024 nt
	global_load_dwordx4 v[38:41], v[2:3], off offset:2048 nt
	global_load_dwordx4 v[34:37], v[2:3], off offset:3072 nt
	v_lshl_add_u64 v[2:3], v[50:51], 0, s[28:29]
	v_lshl_add_u64 v[64:65], v[50:51], 0, s[24:25]
	global_load_dwordx4 v[30:33], v[2:3], off nt
	global_load_dwordx4 v[26:29], v[2:3], off offset:1024 nt
	global_load_dwordx4 v[22:25], v[2:3], off offset:2048 nt
	global_load_dwordx4 v[18:21], v[2:3], off offset:3072 nt
	global_load_dwordx4 v[14:17], v[64:65], off nt
	global_load_dwordx4 v[10:13], v[64:65], off offset:1024 nt
	global_load_dwordx4 v[6:9], v[64:65], off offset:2048 nt
	s_nop 0
	global_load_dwordx4 v[2:5], v[64:65], off offset:3072 nt
	v_cmp_lt_i32_e32 vcc, v58, v57
	s_lshl_b64 s[24:25], s[10:11], 11
	s_waitcnt vmcnt(15)
	v_mul_f32_e32 v66, v71, v71
	v_mul_f32_e32 v67, v73, v73
	s_waitcnt vmcnt(14)
	v_mul_f32_e32 v68, v75, v75
	v_mul_f32_e32 v69, v77, v77
	s_waitcnt vmcnt(13)
	v_mul_f32_e32 v86, v79, v79
	v_mul_f32_e32 v87, v81, v81
	v_fmac_f32_e32 v66, v70, v70
	v_fmac_f32_e32 v67, v72, v72
	v_fmac_f32_e32 v68, v74, v74
	v_fmac_f32_e32 v69, v76, v76
	s_waitcnt vmcnt(12)
	v_mul_f32_e32 v88, v83, v83
	v_mul_f32_e32 v89, v85, v85
	v_fmac_f32_e32 v86, v78, v78
	v_fmac_f32_e32 v87, v80, v80
	v_add_f32_e32 v66, v66, v67
	v_add_f32_e32 v67, v68, v69
	v_fmac_f32_e32 v88, v82, v82
	v_fmac_f32_e32 v89, v84, v84
	v_add_f32_e32 v68, v86, v87
	v_add_f32_e32 v66, v66, v67
	v_cndmask_b32_e32 v64, v56, v58, vcc
	v_add_f32_e32 v69, v88, v89
	v_add_f32_e32 v66, v66, v68
	v_lshlrev_b32_e32 v64, 2, v64
	v_add_f32_e32 v66, v66, v69
	ds_bpermute_b32 v67, v64, v66
	v_cmp_lt_i32_e32 vcc, v59, v57
	v_cvt_pk_bf16_f32 v70, v70, v71
	v_cvt_pk_bf16_f32 v71, v72, v73
	s_waitcnt lgkmcnt(0)
	v_add_f32_e32 v66, v66, v67
	v_cndmask_b32_e32 v65, v56, v59, vcc
	v_lshlrev_b32_e32 v65, 2, v65
	ds_bpermute_b32 v67, v65, v66
	v_cmp_lt_i32_e32 vcc, v60, v57
	s_waitcnt lgkmcnt(0)
	v_add_f32_e32 v89, v66, v67
	v_cndmask_b32_e32 v68, v56, v60, vcc
	v_lshlrev_b32_e32 v68, 2, v68
	ds_bpermute_b32 v90, v68, v89
	v_cmp_lt_i32_e32 vcc, v61, v57
	s_nop 1
	v_cndmask_b32_e32 v69, v56, v61, vcc
	v_lshlrev_b32_e32 v67, 2, v69
	s_waitcnt lgkmcnt(0)
	v_add_f32_e32 v69, v89, v90
	ds_bpermute_b32 v89, v67, v69
	v_cmp_lt_i32_e32 vcc, v62, v57
	s_waitcnt lgkmcnt(0)
	v_add_f32_e32 v69, v69, v89
	v_cndmask_b32_e32 v86, v56, v62, vcc
	v_lshlrev_b32_e32 v66, 2, v86
	v_lshl_add_u64 v[86:87], v[52:53], 0, s[24:25]
	global_store_dwordx2 v[86:87], v[70:71], off
	v_cvt_pk_bf16_f32 v70, v74, v75
	ds_bpermute_b32 v74, v66, v69
	v_cmp_lt_i32_e32 vcc, v63, v57
	v_cvt_pk_bf16_f32 v71, v76, v77
	global_store_dwordx2 v[86:87], v[70:71], off offset:512
	v_cvt_pk_bf16_f32 v72, v78, v79
	s_waitcnt lgkmcnt(0)
	v_add_f32_e32 v70, v69, v74
	v_cndmask_b32_e32 v88, v56, v63, vcc
	v_lshlrev_b32_e32 v69, 2, v88
	ds_bpermute_b32 v71, v69, v70
	v_cvt_pk_bf16_f32 v73, v80, v81
	global_store_dwordx2 v[86:87], v[72:73], off offset:1024
	v_cvt_pk_bf16_f32 v72, v82, v83
	v_cvt_pk_bf16_f32 v73, v84, v85
	global_store_dwordx2 v[86:87], v[72:73], off offset:1536
	s_and_saveexec_b64 s[24:25], s[4:5]
	s_cbranch_execz .LBB0_19
	s_lshl_b64 s[28:29], s[10:11], 6
	s_waitcnt lgkmcnt(0)
	v_add_f32_e32 v70, v70, v71
	v_lshl_add_u64 v[72:73], v[54:55], 0, s[28:29]
	v_cndmask_b32_e64 v70, 0, v70, s[6:7]
	global_store_dword v[72:73], v70, off
	s_or_b64 exec, exec, s[24:25]
	s_andn2_b64 vcc, exec, s[22:23]
	s_cbranch_vccz .LBB0_20
